# static GEMM priority raise on the other wave half (wr=0) for comparison with the wr=1 build
# speedup vs baseline: 1.0283x; 1.0093x over previous
; #define PG8_STAGE(bufoff, gbase, voff) do { _Pragma("unroll") for (int _i = 0; _i < 2; ++_i) \
;         __builtin_amdgcn_global_load_lds((const unsigned*)((const char*)(gbase) + (voff)[_i]), (LAS unsigned*)(lds + (bufoff) + ldsw + _i * 8192), 16, 0, 0); } while (0)
; #define PG8_WAIT_V(n) asm volatile("s_waitcnt vmcnt(" #n ")" ::: "memory")
; #define PG8_BAR __builtin_amdgcn_s_barrier()
; template <class Epi>
; __device__ __forceinline__ void gemm_phase(LAS unsigned char* lds, const Gemm g, const StaticOrder& S, const Epi& E) {
;     const int tid = threadIdx.x, wid = __builtin_amdgcn_readfirstlane(tid >> 6), lane = tid & 63, wr = wid >> 2, wc = wid & 3, fr = lane & 15, fq = lane >> 4;
;     const int K = g.K, nt = K / BK;
;     unsigned voffA[2], voffB[2];
; #pragma unroll
;     for (int i = 0; i < 2; ++i) { int R, C; stage_rc(tid * 16 + i * 8192, R, C); const int Rb = Epi::PERM ? ((R & ~31) + perm32(R & 31)) : R;
;         voffA[i] = (unsigned)(R * K + C) * 2u; voffB[i] = (unsigned)(Rb * K + C) * 2u; }
;     const size_t kstep = (size_t)(BK * 2);
;     const size_t hstep = (size_t)HALF * K * 2;
;     const size_t tstep = 2 * hstep;
;     const unsigned ldsw = (unsigned)wid * 1024u;
;     const int aoff = lds_byte(wr * 64 + fr, fq * 8), boff = lds_byte(wc * 32 + fr, fq * 8);
;     ...
;     Unit cur, nxt; int ui = 0;
;     if (!S.next(0, cur)) return;
;     f32x4 acc[2][2][4][2];
; #pragma unroll
;     for (int a = 0; a < 2; ++a)
; #pragma unroll
;         for (int b = 0; b < 2; ++b)
; #pragma unroll
;             for (int m = 0; m < 4; ++m)
; #pragma unroll
;                 for (int n = 0; n < 2; ++n) acc[a][b][m][n] = (f32x4){0.f, 0.f, 0.f, 0.f};
;     bf16x8 At[4][2], B0[2][2], B1[2][2];
;     const char* cA = (const char*)g.A + (size_t)cur.pm * tstep; const char* cB = (const char*)g.Bt + (size_t)cur.pn * tstep;
;     PG8_STAGE(PG8_SB(0, 0), cB, voffB); PG8_STAGE(PG8_SA(0, 0), cA, voffA); PG8_STAGE(PG8_SB(0, 1), cB + hstep, voffB); PG8_STAGE(PG8_SA(0, 1), cA + hstep, voffA);
;     if (wr == 1) PG8_BAR;
;     PG8_WAIT_V(4); PG8_BAR;
;     PG8_STAGE(PG8_SB(1, 0), cB + kstep, voffB); PG8_STAGE(PG8_SA(1, 0), cA + kstep, voffA); PG8_STAGE(PG8_SB(1, 1), cB + hstep + kstep, voffB);
;     PG8_WAIT_V(6); PG8_BAR;
.LBB0_72:
	v_lshrrev_b32_e32 v165, 1, v133
	v_and_b32_e32 v158, 24, v165
	v_lshlrev_b32_e32 v0, 6, v133
	v_lshlrev_b32_e32 v162, 1, v158
	v_and_b32_e32 v0, 0x3c0, v0
	v_and_b32_e32 v1, 32, v134
	s_mov_b32 s2, s40
	v_readfirstlane_b32 s34, v133
	v_and_b32_e32 v161, 15, v133
	v_bitop3_b32 v163, v162, v1, v0 bitop3:0x36
	s_cmpk_gt_i32 s40, 0xf67
	v_bfe_u32 v168, v133, 2, 2
	v_bfe_u32 v160, v133, 2, 4
	v_lshrrev_b32_e32 v169, 5, v133
	v_lshlrev_b32_e32 v166, 4, v133
	v_and_b32_e32 v167, 32, v133
	v_and_b32_e32 v159, 64, v133
	v_lshrrev_b32_e32 v164, 3, v133
	v_writelane_b32 v244, s2, 6
	s_nop 1
	v_writelane_b32 v244, s3, 7
	s_cbranch_scc1 .LBB0_96
	v_and_b32_e32 v0, 4, v169
	v_and_b32_e32 v1, 24, v165
	v_add_u32_e32 v8, 0x2000, v166
	v_or3_b32 v0, v0, v168, v1
	v_lshrrev_b32_e32 v1, 7, v8
	s_movk_i32 s6, 0xe0
	v_and_or_b32 v2, v1, s6, v0
	s_movk_i32 s6, 0xf0
	v_bitop3_b32 v9, v166, v167, 48 bitop3:0x6c
	v_and_or_b32 v1, v1, s6, v160
	s_movk_i32 s6, 0x60
	v_or_b32_e32 v3, v9, v159
	v_and_or_b32 v0, v164, s6, v0
	s_movk_i32 s6, 0x70
	s_mov_b32 s8, s40
	s_ashr_i32 s40, s40, 31
	v_lshl_or_b32 v140, v0, 12, v3
	v_and_or_b32 v0, v164, s6, v160
	s_lshr_b32 s6, s40, 29
	s_add_i32 s6, s8, s6
	s_lshr_b32 s9, s34, 6
	s_ashr_i32 s7, s6, 3
	s_and_b32 s6, s6, -8
	s_lshr_b32 s10, s34, 8
	s_lshl_b32 s35, s9, 10
	s_sub_i32 s6, s8, s6
	s_cmp_lt_i32 s6, 0
	s_movk_i32 s41, 0x1ee
	s_cselect_b32 s8, s41, 0x1ed
	s_mul_i32 s6, s8, s6
	s_add_i32 s6, s6, s7
	s_mul_hi_i32 s7, s6, 0x8d3dcb09
	s_add_i32 s7, s7, s6
	s_lshr_b32 s8, s7, 31
	s_ashr_i32 s7, s7, 7
	s_add_i32 s7, s7, s8
	s_lshl_b32 s11, s7, 3
	s_mulk_i32 s7, 0xe8
	s_sub_i32 s6, s6, s7
	s_sext_i32_i16 s7, s6
	s_bfe_u32 s7, s7, 0x3001c
	s_add_i32 s7, s6, s7
	s_sext_i32_i16 s8, s7
	s_and_b32 s7, s7, 0xfff8
	s_load_dwordx2 s[2:3], s[0:1], 0xc0
	s_load_dwordx2 s[4:5], s[0:1], 0xd0
	s_sub_i32 s6, s6, s7
	s_sext_i32_i16 s6, s6
	s_lshr_b32 s8, s8, 3
	s_add_i32 s6, s11, s6
	s_ashr_i32 s7, s6, 31
	s_bfe_i64 s[14:15], s[8:9], 0x100000
	s_lshl_b64 s[12:13], s[6:7], 20
	s_lshl_b64 s[14:15], s[14:15], 20
	s_waitcnt lgkmcnt(0)
	s_add_u32 s18, s4, s14
	s_addc_u32 s19, s5, s15
	s_add_i32 s42, s35, 0
	s_add_i32 m0, s42, 0x10000
	v_lshl_or_b32 v136, v2, 12, v3
	global_load_lds_dwordx4 v140, s[18:19]
	s_add_i32 m0, s42, 0x12000
	s_add_u32 s20, s2, s12
	v_lshl_or_b32 v142, v0, 12, v3
	global_load_lds_dwordx4 v136, s[18:19]
	s_addc_u32 s21, s3, s13
	s_mov_b32 m0, s42
	s_add_i32 s43, s42, 0x2000
	v_lshl_or_b32 v138, v1, 12, v3
	global_load_lds_dwordx4 v142, s[20:21]
	s_mov_b32 m0, s43
	s_add_u32 s12, s18, 0x80000
	global_load_lds_dwordx4 v138, s[20:21]
	s_addc_u32 s13, s19, 0
	s_add_i32 m0, s42, 0x14000
	v_mov_b32_e32 v145, 0
	global_load_lds_dwordx4 v140, s[12:13]
	s_add_i32 m0, s42, 0x16000
	v_mov_b32_e32 v141, v145
	global_load_lds_dwordx4 v136, s[12:13]
	s_add_u32 s12, s20, 0x80000
	s_addc_u32 s13, s21, 0
	s_add_i32 s44, s42, 0x4000
	s_mov_b32 m0, s44
	s_add_i32 s45, s42, 0x6000
	global_load_lds_dwordx4 v142, s[12:13]
	s_mov_b32 m0, s45
	v_mov_b32_e32 v137, v145
	global_load_lds_dwordx4 v138, s[12:13]
	s_load_dwordx4 s[12:15], s[0:1], 0xb0
	v_mov_b32_e32 v143, v145
	v_mov_b32_e32 v139, v145
	s_mov_b32 s46, 0
	v_lshl_add_u64 v[6:7], s[18:19], 0, v[140:141]
	v_lshl_add_u64 v[4:5], s[18:19], 0, v[136:137]
	v_lshl_add_u64 v[2:3], s[20:21], 0, v[142:143]
	s_cmp_lg_u32 s10, 1
	v_lshl_add_u64 v[0:1], s[20:21], 0, v[138:139]
	s_cbranch_scc1 .LBB0_75
	s_barrier
	s_branch .Lg1_prio_done
.LBB0_75:
	s_setprio 1

; #define PG8_STAGE(bufoff, gbase, voff) do { _Pragma("unroll") for (int _i = 0; _i < 2; ++_i) \
;         __builtin_amdgcn_global_load_lds((const unsigned*)((const char*)(gbase) + (voff)[_i]), (LAS unsigned*)(lds + (bufoff) + ldsw + _i * 8192), 16, 0, 0); } while (0)
; #define PG8_WAIT_V(n) asm volatile("s_waitcnt vmcnt(" #n ")" ::: "memory")
; #define PG8_BAR __builtin_amdgcn_s_barrier()
; template <class Epi>
; __device__ __forceinline__ void gemm_phase(LAS unsigned char* lds, const Gemm g, const StaticOrder& S, const Epi& E) {
;     const int tid = threadIdx.x, wid = __builtin_amdgcn_readfirstlane(tid >> 6), lane = tid & 63, wr = wid >> 2, wc = wid & 3, fr = lane & 15, fq = lane >> 4;
;     const int K = g.K, nt = K / BK;
;     unsigned voffA[2], voffB[2];
; #pragma unroll
;     for (int i = 0; i < 2; ++i) { int R, C; stage_rc(tid * 16 + i * 8192, R, C); const int Rb = Epi::PERM ? ((R & ~31) + perm32(R & 31)) : R;
;         voffA[i] = (unsigned)(R * K + C) * 2u; voffB[i] = (unsigned)(Rb * K + C) * 2u; }
;     const size_t kstep = (size_t)(BK * 2);
;     const size_t hstep = (size_t)HALF * K * 2;
;     const size_t tstep = 2 * hstep;
;     const unsigned ldsw = (unsigned)wid * 1024u;
;     const int aoff = lds_byte(wr * 64 + fr, fq * 8), boff = lds_byte(wc * 32 + fr, fq * 8);
;     ...
;     Unit cur, nxt; int ui = 0;
;     if (!S.next(0, cur)) return;
;     f32x4 acc[2][2][4][2];
; #pragma unroll
;     for (int a = 0; a < 2; ++a)
; #pragma unroll
;         for (int b = 0; b < 2; ++b)
; #pragma unroll
;             for (int m = 0; m < 4; ++m)
; #pragma unroll
;                 for (int n = 0; n < 2; ++n) acc[a][b][m][n] = (f32x4){0.f, 0.f, 0.f, 0.f};
;     bf16x8 At[4][2], B0[2][2], B1[2][2];
;     const char* cA = (const char*)g.A + (size_t)cur.pm * tstep; const char* cB = (const char*)g.Bt + (size_t)cur.pn * tstep;
;     PG8_STAGE(PG8_SB(0, 0), cB, voffB); PG8_STAGE(PG8_SA(0, 0), cA, voffA); PG8_STAGE(PG8_SB(0, 1), cB + hstep, voffB); PG8_STAGE(PG8_SA(0, 1), cA + hstep, voffA);
;     if (wr == 1) PG8_BAR;
;     PG8_WAIT_V(4); PG8_BAR;
;     PG8_STAGE(PG8_SB(1, 0), cB + kstep, voffB); PG8_STAGE(PG8_SA(1, 0), cA + kstep, voffA); PG8_STAGE(PG8_SB(1, 1), cB + hstep + kstep, voffB);
;     PG8_WAIT_V(6); PG8_BAR;
.LBB0_552:
	s_or_b64 exec, exec, s[2:3]
	s_cmpk_gt_i32 s40, 0x43f
	v_readfirstlane_b32 s42, v133
	s_barrier
	s_cbranch_scc1 .LBB0_564
	s_waitcnt vmcnt(2)
	v_and_b32_e32 v0, 4, v169
	v_and_b32_e32 v1, 24, v165
	s_waitcnt vmcnt(0)
	v_add_u32_e32 v8, 0x2000, v166
	v_or3_b32 v0, v0, v168, v1
	v_lshrrev_b32_e32 v1, 7, v8
	s_movk_i32 s8, 0xe0
	v_and_or_b32 v2, v1, s8, v0
	s_movk_i32 s8, 0xf0
	v_bitop3_b32 v9, v166, v167, 48 bitop3:0x6c
	v_and_or_b32 v1, v1, s8, v160
	s_movk_i32 s8, 0x60
	v_or_b32_e32 v3, v9, v159
	v_and_or_b32 v0, v164, s8, v0
	s_movk_i32 s8, 0x70
	s_ashr_i32 s44, s40, 31
	v_lshl_or_b32 v138, v0, 12, v3
	v_and_or_b32 v0, v164, s8, v160
	s_lshr_b32 s8, s44, 29
	s_add_i32 s8, s40, s8
	s_lshr_b32 s12, s42, 6
	s_ashr_i32 s10, s8, 3
	s_and_b32 s8, s8, -8
	s_lshr_b32 s9, s42, 8
	s_lshl_b32 s43, s12, 10
	s_sub_i32 s8, s40, s8
	s_cmp_lt_i32 s8, 0
	s_movk_i32 s45, 0x89
	s_cselect_b32 s11, s45, 0x88
	s_mul_i32 s8, s11, s8
	s_add_i32 s8, s8, s10
	s_ashr_i32 s10, s8, 31
	s_lshr_b32 s10, s10, 26
	s_add_i32 s10, s8, s10
	s_ashr_i32 s11, s10, 6
	s_and_b32 s10, s10, 0xffc0
	s_sub_i32 s10, s8, s10
	s_bfe_i32 s8, s10, 0x80000
	s_bfe_u32 s8, s8, 0x3000c
	s_add_i32 s13, s10, s8
	s_bfe_i32 s8, s13, 0x80000
	s_and_b32 s13, s13, 0xf8
	s_sub_i32 s10, s10, s13
	s_load_dwordx2 s[2:3], s[0:1], 0xc8
	s_load_dwordx2 s[4:5], s[0:1], 0xd8
	s_load_dwordx2 s[6:7], s[0:1], 0xe8
	s_lshl_b32 s11, s11, 3
	s_sext_i32_i16 s8, s8
	s_sext_i32_i8 s10, s10
	s_lshr_b32 s8, s8, 3
	s_add_i32 s20, s11, s10
	s_ashr_i32 s21, s20, 31
	s_bfe_i64 s[14:15], s[8:9], 0x100000
	s_lshl_b64 s[10:11], s[20:21], 20
	s_lshl_b64 s[14:15], s[14:15], 20
	s_waitcnt lgkmcnt(0)
	s_add_u32 s34, s4, s14
	s_addc_u32 s35, s5, s15
	s_add_i32 s21, s43, 0
	s_add_i32 m0, s21, 0x10000
	v_lshl_or_b32 v134, v2, 12, v3
	global_load_lds_dwordx4 v138, s[34:35]
	s_add_i32 m0, s21, 0x12000
	s_add_u32 s30, s2, s10
	v_lshl_or_b32 v140, v0, 12, v3
	global_load_lds_dwordx4 v134, s[34:35]
	s_addc_u32 s31, s3, s11
	s_mov_b32 m0, s21
	s_add_i32 s46, s21, 0x2000
	v_lshl_or_b32 v136, v1, 12, v3
	global_load_lds_dwordx4 v140, s[30:31]
	s_mov_b32 m0, s46
	s_add_u32 s10, s34, 0x80000
	global_load_lds_dwordx4 v136, s[30:31]
	s_addc_u32 s11, s35, 0
	s_add_i32 m0, s21, 0x14000
	v_mov_b32_e32 v139, 0
	global_load_lds_dwordx4 v138, s[10:11]
	s_add_i32 m0, s21, 0x16000
	v_mov_b32_e32 v135, v139
	global_load_lds_dwordx4 v134, s[10:11]
	s_add_u32 s10, s30, 0x80000
	s_addc_u32 s11, s31, 0
	s_add_i32 s47, s21, 0x4000
	s_mov_b32 m0, s47
	s_add_i32 s48, s21, 0x6000
	global_load_lds_dwordx4 v140, s[10:11]
	s_mov_b32 m0, s48
	v_mov_b32_e32 v141, v139
	global_load_lds_dwordx4 v136, s[10:11]
	v_mov_b32_e32 v137, v139
	s_mov_b32 s49, 0
	v_lshl_add_u64 v[6:7], s[34:35], 0, v[138:139]
	v_lshl_add_u64 v[4:5], s[34:35], 0, v[134:135]
	v_lshl_add_u64 v[2:3], s[30:31], 0, v[140:141]
	v_lshl_add_u64 v[0:1], s[30:31], 0, v[136:137]
	s_cmp_lg_u32 s9, 1
	s_mov_b64 s[10:11], 0x80000
	s_cbranch_scc1 .LBB0_555
	s_barrier
	s_branch .Lg2_prio_done
